# NSA phase: query blocks dealt to workgroups by cost (workgroups owning a cheap block qb<16 also take the three largest remaining blocks; the others take four blocks from 16..79 with equal sums)
# speedup vs baseline: 1.0024x; 1.0002x over previous
.LBB0_1252:
	s_mul_i32 s4, s63, 3
	s_sub_i32 s5, 0x7f, s4
	s_sub_i32 s8, 0x7e, s4
	s_sub_i32 s4, 0x7d, s4
	s_xor_b32 s81, s63, 63
	s_add_i32 s82, s63, 32
	s_sub_i32 s83, 0x5f, s63
	s_cmp_lt_u32 s63, 16
	s_cselect_b32 s81, s5, s81
	s_cselect_b32 s82, s8, s82
	s_cselect_b32 s83, s4, s83
	v_mov_b32_e32 v210, v197
	s_mov_b64 s[8:9], s[0:1]
	s_load_dwordx2 s[4:5], s[8:9], 0x10
	v_and_b32_e32 v227, 3, v210
	v_or_b32_e32 v4, s29, v227
	v_lshlrev_b32_e32 v2, 2, v4
	s_cmp_lt_i32 s95, 1
	s_waitcnt lgkmcnt(0)
	global_load_dword v5, v2, s[4:5] offset:1984
	s_mov_b32 s44, s63
	s_cbranch_scc1 .LBB0_1257
	s_cmp_lg_u32 s95, 1
	s_mov_b64 s[8:9], -1
	s_cbranch_scc0 .LBB0_1255
	s_cmp_eq_u32 s95, 2
	s_cselect_b32 s44, s82, s83
	s_mov_b64 s[8:9], 0
